# conva_tile 31-tap conv: the row's 16 LDS reads issued together into distinct registers with one wait (same fma/add order)
# speedup vs baseline: 1.0125x; 1.0125x over previous
; DI void lds_barrier() { asm volatile("s_waitcnt lgkmcnt(0)" ::: "memory"); __builtin_amdgcn_s_barrier(); asm volatile("" ::: "memory"); }
; DI void conva_tile(CP c, int l, int tile, float* U) {
;     ...
;     for (int tt = 0; tt < RT; ++tt) { float acc = bias;
; #pragma unroll
;         for (int i = 0; i < 31; ++i) acc += w[i] * U[(tt + i) * 512 + ch];
;         U[tt * 512 + ch] = acc; }
;     lds_barrier();
;     {
;         float v[4][8], sm[4], qv[4];
; #pragma unroll
;         for (int k = 0; k < 4; ++k) { const int tt = wave + 8 * k; sm[k] = 0.f;
;             if (tt < RT) { const f32x4 a = *(const f32x4*)(U + tt * 512 + lane * 8), bq = *(const f32x4*)(U + tt * 512 + lane * 8 + 4);
;                 v[k][0] = a[0]; v[k][1] = a[1]; v[k][2] = a[2]; v[k][3] = a[3]; v[k][4] = bq[0]; v[k][5] = bq[1]; v[k][6] = bq[2]; v[k][7] = bq[3]; }
.LBB0_1014:
	ds_read2st64_b32 v[82:83], v0 offset1:8
	ds_read2st64_b32 v[84:85], v0 offset0:16 offset1:24
	ds_read2st64_b32 v[86:87], v0 offset0:32 offset1:40
	ds_read2st64_b32 v[88:89], v0 offset0:48 offset1:56
	ds_read2st64_b32 v[90:91], v0 offset0:64 offset1:72
	ds_read2st64_b32 v[92:93], v0 offset0:80 offset1:88
	ds_read2st64_b32 v[94:95], v0 offset0:96 offset1:104
	ds_read2st64_b32 v[96:97], v0 offset0:112 offset1:120
	ds_read2st64_b32 v[98:99], v0 offset0:128 offset1:136
	ds_read2st64_b32 v[100:101], v0 offset0:144 offset1:152
	ds_read2st64_b32 v[102:103], v0 offset0:160 offset1:168
	ds_read2st64_b32 v[104:105], v0 offset0:176 offset1:184
	ds_read2st64_b32 v[106:107], v0 offset0:192 offset1:200
	ds_read2st64_b32 v[108:109], v0 offset0:208 offset1:216
	ds_read2st64_b32 v[110:111], v0 offset0:224 offset1:232
	ds_read_b32 v112, v0 offset:61440
	v_add_u32_e32 v40, 0x800, v0
	s_add_i32 s18, s18, -1
	s_cmp_lg_u32 s18, 0
	s_waitcnt vmcnt(0) lgkmcnt(0)
	v_fma_f32 v35, v27, v82, v34
	v_fmac_f32_e32 v35, v28, v83
	v_fmac_f32_e32 v35, v11, v84
	v_fmac_f32_e32 v35, v29, v85
	v_fmac_f32_e32 v35, v16, v86
	v_fmac_f32_e32 v35, v17, v87
	v_fmac_f32_e32 v35, v18, v88
	v_fmac_f32_e32 v35, v30, v89
	v_fmac_f32_e32 v35, v19, v90
	v_fmac_f32_e32 v35, v20, v91
	v_fmac_f32_e32 v35, v21, v92
	v_fmac_f32_e32 v35, v31, v93
	v_fmac_f32_e32 v35, v22, v94
	v_fmac_f32_e32 v35, v23, v95
	v_fmac_f32_e32 v35, v24, v96
	v_fmac_f32_e32 v35, v32, v97
	v_fmac_f32_e32 v35, v25, v98
	v_fmac_f32_e32 v35, v26, v99
	v_fmac_f32_e32 v35, v33, v100
	v_mul_f32_e32 v113, v2, v101
	v_add_f32_e32 v35, v35, v113
	v_mul_f32_e32 v113, v3, v102
	v_add_f32_e32 v35, v35, v113
	v_mul_f32_e32 v113, v4, v103
	v_add_f32_e32 v35, v35, v113
	v_mul_f32_e32 v113, v5, v104
	v_add_f32_e32 v35, v35, v113
	v_mul_f32_e32 v113, v6, v105
	v_add_f32_e32 v35, v35, v113
	v_mul_f32_e32 v113, v7, v106
	v_add_f32_e32 v35, v35, v113
	v_mul_f32_e32 v113, v8, v107
	v_add_f32_e32 v35, v35, v113
	v_mul_f32_e32 v113, v9, v108
	v_add_f32_e32 v35, v35, v113
	v_mul_f32_e32 v113, v12, v109
	v_add_f32_e32 v35, v35, v113
	v_mul_f32_e32 v113, v13, v110
	v_add_f32_e32 v35, v35, v113
	v_mul_f32_e32 v113, v14, v111
	v_add_f32_e32 v35, v35, v113
	v_mul_f32_e32 v113, v15, v112
	v_add_f32_e32 v35, v35, v113
	ds_write_b32 v0, v35
	v_mov_b32_e32 v0, v40
	s_cbranch_scc1 .LBB0_1014
	s_waitcnt lgkmcnt(0)
	s_barrier
	v_and_b32_e32 v56, 63, v10
	v_ashrrev_i32_e32 v55, 6, v10
	v_lshl_add_u32 v0, v56, 5, 0
	v_cmp_gt_i32_e64 s[42:43], s36, v55
	v_mov_b32_e32 v4, 0
	v_mov_b32_e32 v8, 0
	v_mov_b32_e32 v9, 0
	v_mov_b32_e32 v6, 0
	v_mov_b32_e32 v7, 0
	v_mov_b32_e32 v12, 0
	v_mov_b32_e32 v13, 0
	v_mov_b32_e32 v10, 0
	v_mov_b32_e32 v11, 0
	s_and_saveexec_b64 s[18:19], s[42:43]
	s_cbranch_execz .LBB0_1017
	v_lshl_add_u32 v2, v55, 11, v0
	ds_read_b128 v[10:13], v2
	ds_read_b128 v[6:9], v2 offset:16
